# plus: filter w3 contraction loop rewritten (software-pipelined global and LDS loads, in-place accumulators)
# speedup vs baseline: 1.0600x; 1.0163x over previous
; __device__ __forceinline__ void filter_item(const Params& p, int l, int Lf, int t0, float* dst, float* hidT  , int wid0) {
;     ...
; #pragma unroll 16
;     for (int j = 0; j < 64; ++j) {
;         const float wa = w3[j * 1024 + tid], wb = w3[j * 1024 + 512 + tid];
; #pragma unroll
;         for (int g = 0; g < 8; ++g) { const f32x4 hv = *(const f32x4*)(hidT + j * 32 + 4 * g);
; #pragma unroll
;             for (int i = 0; i < 4; ++i) { acc0[4 * g + i] += hv[i] * wa; acc1[4 * g + i] += hv[i] * wb; } }
;     }
.LBB0_719:
	s_waitcnt vmcnt(0)
	v_add_u32_e32 v182, 0xffffc200, v4
	v_ashrrev_i32_e32 v183, 31, v182
	v_lshl_add_u64 v[182:183], v[182:183], 2, s[72:73]
	s_mov_b64 vcc, 0x1000
	global_load_dword v174, v[182:183], off
	global_load_dword v176, v[182:183], off offset:2048
	v_lshl_add_u64 v[182:183], v[182:183], 0, vcc
	global_load_dword v178, v[182:183], off
	global_load_dword v180, v[182:183], off offset:2048
	v_lshl_add_u64 v[182:183], v[182:183], 0, vcc
	s_add_i32 s1, s0, 0x1b800
	v_mov_b32_e32 v186, s1
	ds_read_b128 v[110:113], v186
	ds_read_b128 v[114:117], v186 offset:16
	ds_read_b128 v[118:121], v186 offset:32
	ds_read_b128 v[122:125], v186 offset:48
	ds_read_b128 v[126:129], v186 offset:64
	ds_read_b128 v[130:133], v186 offset:80
	ds_read_b128 v[134:137], v186 offset:96
	ds_read_b128 v[138:141], v186 offset:112
	s_movk_i32 s1, 31
.Lw3_0_loop:
	ds_read_b128 v[142:145], v186 offset:128
	ds_read_b128 v[146:149], v186 offset:144
	ds_read_b128 v[150:153], v186 offset:160
	ds_read_b128 v[154:157], v186 offset:176
	ds_read_b128 v[158:161], v186 offset:192
	ds_read_b128 v[162:165], v186 offset:208
	ds_read_b128 v[166:169], v186 offset:224
	ds_read_b128 v[170:173], v186 offset:240
	s_waitcnt vmcnt(2) lgkmcnt(8)
	v_pk_fma_f32 v[68:69], v[174:175], v[110:111], v[68:69] op_sel_hi:[0,1,1]
	v_pk_fma_f32 v[62:63], v[176:177], v[110:111], v[62:63] op_sel_hi:[0,1,1]
	v_pk_fma_f32 v[66:67], v[174:175], v[112:113], v[66:67] op_sel_hi:[0,1,1]
	v_pk_fma_f32 v[64:65], v[176:177], v[112:113], v[64:65] op_sel_hi:[0,1,1]
	v_pk_fma_f32 v[60:61], v[174:175], v[114:115], v[60:61] op_sel_hi:[0,1,1]
	v_pk_fma_f32 v[56:57], v[176:177], v[114:115], v[56:57] op_sel_hi:[0,1,1]
	v_pk_fma_f32 v[58:59], v[174:175], v[116:117], v[58:59] op_sel_hi:[0,1,1]
	v_pk_fma_f32 v[54:55], v[176:177], v[116:117], v[54:55] op_sel_hi:[0,1,1]
	v_pk_fma_f32 v[52:53], v[174:175], v[118:119], v[52:53] op_sel_hi:[0,1,1]
	v_pk_fma_f32 v[48:49], v[176:177], v[118:119], v[48:49] op_sel_hi:[0,1,1]
	v_pk_fma_f32 v[50:51], v[174:175], v[120:121], v[50:51] op_sel_hi:[0,1,1]
	v_pk_fma_f32 v[46:47], v[176:177], v[120:121], v[46:47] op_sel_hi:[0,1,1]
	v_pk_fma_f32 v[44:45], v[174:175], v[122:123], v[44:45] op_sel_hi:[0,1,1]
	v_pk_fma_f32 v[40:41], v[176:177], v[122:123], v[40:41] op_sel_hi:[0,1,1]
	v_pk_fma_f32 v[42:43], v[174:175], v[124:125], v[42:43] op_sel_hi:[0,1,1]
	v_pk_fma_f32 v[38:39], v[176:177], v[124:125], v[38:39] op_sel_hi:[0,1,1]
	v_pk_fma_f32 v[36:37], v[174:175], v[126:127], v[36:37] op_sel_hi:[0,1,1]
	v_pk_fma_f32 v[32:33], v[176:177], v[126:127], v[32:33] op_sel_hi:[0,1,1]
	v_pk_fma_f32 v[34:35], v[174:175], v[128:129], v[34:35] op_sel_hi:[0,1,1]
	v_pk_fma_f32 v[30:31], v[176:177], v[128:129], v[30:31] op_sel_hi:[0,1,1]
	v_pk_fma_f32 v[28:29], v[174:175], v[130:131], v[28:29] op_sel_hi:[0,1,1]
	v_pk_fma_f32 v[24:25], v[176:177], v[130:131], v[24:25] op_sel_hi:[0,1,1]
	v_pk_fma_f32 v[26:27], v[174:175], v[132:133], v[26:27] op_sel_hi:[0,1,1]
	v_pk_fma_f32 v[22:23], v[176:177], v[132:133], v[22:23] op_sel_hi:[0,1,1]
	v_pk_fma_f32 v[20:21], v[174:175], v[134:135], v[20:21] op_sel_hi:[0,1,1]
	v_pk_fma_f32 v[14:15], v[176:177], v[134:135], v[14:15] op_sel_hi:[0,1,1]
	v_pk_fma_f32 v[18:19], v[174:175], v[136:137], v[18:19] op_sel_hi:[0,1,1]
	v_pk_fma_f32 v[16:17], v[176:177], v[136:137], v[16:17] op_sel_hi:[0,1,1]
	v_pk_fma_f32 v[10:11], v[174:175], v[138:139], v[10:11] op_sel_hi:[0,1,1]
	v_pk_fma_f32 v[6:7], v[176:177], v[138:139], v[6:7] op_sel_hi:[0,1,1]
	v_pk_fma_f32 v[12:13], v[174:175], v[140:141], v[12:13] op_sel_hi:[0,1,1]
	v_pk_fma_f32 v[8:9], v[176:177], v[140:141], v[8:9] op_sel_hi:[0,1,1]
	global_load_dword v174, v[182:183], off
	global_load_dword v176, v[182:183], off offset:2048
	v_lshl_add_u64 v[182:183], v[182:183], 0, vcc
	ds_read_b128 v[110:113], v186 offset:256
	ds_read_b128 v[114:117], v186 offset:272
	ds_read_b128 v[118:121], v186 offset:288
	ds_read_b128 v[122:125], v186 offset:304
	ds_read_b128 v[126:129], v186 offset:320
	ds_read_b128 v[130:133], v186 offset:336
	ds_read_b128 v[134:137], v186 offset:352
	ds_read_b128 v[138:141], v186 offset:368
	s_waitcnt vmcnt(2) lgkmcnt(8)
	v_pk_fma_f32 v[68:69], v[178:179], v[142:143], v[68:69] op_sel_hi:[0,1,1]
	v_pk_fma_f32 v[62:63], v[180:181], v[142:143], v[62:63] op_sel_hi:[0,1,1]
	v_pk_fma_f32 v[66:67], v[178:179], v[144:145], v[66:67] op_sel_hi:[0,1,1]
	v_pk_fma_f32 v[64:65], v[180:181], v[144:145], v[64:65] op_sel_hi:[0,1,1]
	v_pk_fma_f32 v[60:61], v[178:179], v[146:147], v[60:61] op_sel_hi:[0,1,1]
	v_pk_fma_f32 v[56:57], v[180:181], v[146:147], v[56:57] op_sel_hi:[0,1,1]
	v_pk_fma_f32 v[58:59], v[178:179], v[148:149], v[58:59] op_sel_hi:[0,1,1]
	v_pk_fma_f32 v[54:55], v[180:181], v[148:149], v[54:55] op_sel_hi:[0,1,1]
	v_pk_fma_f32 v[52:53], v[178:179], v[150:151], v[52:53] op_sel_hi:[0,1,1]
	v_pk_fma_f32 v[48:49], v[180:181], v[150:151], v[48:49] op_sel_hi:[0,1,1]
	v_pk_fma_f32 v[50:51], v[178:179], v[152:153], v[50:51] op_sel_hi:[0,1,1]
	v_pk_fma_f32 v[46:47], v[180:181], v[152:153], v[46:47] op_sel_hi:[0,1,1]
	v_pk_fma_f32 v[44:45], v[178:179], v[154:155], v[44:45] op_sel_hi:[0,1,1]
	v_pk_fma_f32 v[40:41], v[180:181], v[154:155], v[40:41] op_sel_hi:[0,1,1]
	v_pk_fma_f32 v[42:43], v[178:179], v[156:157], v[42:43] op_sel_hi:[0,1,1]
	v_pk_fma_f32 v[38:39], v[180:181], v[156:157], v[38:39] op_sel_hi:[0,1,1]
	v_pk_fma_f32 v[36:37], v[178:179], v[158:159], v[36:37] op_sel_hi:[0,1,1]
	v_pk_fma_f32 v[32:33], v[180:181], v[158:159], v[32:33] op_sel_hi:[0,1,1]
	v_pk_fma_f32 v[34:35], v[178:179], v[160:161], v[34:35] op_sel_hi:[0,1,1]
	v_pk_fma_f32 v[30:31], v[180:181], v[160:161], v[30:31] op_sel_hi:[0,1,1]
	v_pk_fma_f32 v[28:29], v[178:179], v[162:163], v[28:29] op_sel_hi:[0,1,1]
	v_pk_fma_f32 v[24:25], v[180:181], v[162:163], v[24:25] op_sel_hi:[0,1,1]
	v_pk_fma_f32 v[26:27], v[178:179], v[164:165], v[26:27] op_sel_hi:[0,1,1]
	v_pk_fma_f32 v[22:23], v[180:181], v[164:165], v[22:23] op_sel_hi:[0,1,1]
	v_pk_fma_f32 v[20:21], v[178:179], v[166:167], v[20:21] op_sel_hi:[0,1,1]
	v_pk_fma_f32 v[14:15], v[180:181], v[166:167], v[14:15] op_sel_hi:[0,1,1]
	v_pk_fma_f32 v[18:19], v[178:179], v[168:169], v[18:19] op_sel_hi:[0,1,1]
	v_pk_fma_f32 v[16:17], v[180:181], v[168:169], v[16:17] op_sel_hi:[0,1,1]
	v_pk_fma_f32 v[10:11], v[178:179], v[170:171], v[10:11] op_sel_hi:[0,1,1]
	v_pk_fma_f32 v[6:7], v[180:181], v[170:171], v[6:7] op_sel_hi:[0,1,1]
	v_pk_fma_f32 v[12:13], v[178:179], v[172:173], v[12:13] op_sel_hi:[0,1,1]
	v_pk_fma_f32 v[8:9], v[180:181], v[172:173], v[8:9] op_sel_hi:[0,1,1]
	global_load_dword v178, v[182:183], off
	global_load_dword v180, v[182:183], off offset:2048
	v_lshl_add_u64 v[182:183], v[182:183], 0, vcc
	v_add_u32_e32 v186, 0x100, v186
	s_add_i32 s1, s1, -1
	s_cmp_lg_u32 s1, 0
	s_cbranch_scc1 .Lw3_0_loop
; __device__ __forceinline__ void filter_item(const Params& p, int l, int Lf, int t0, float* dst, float* hidT  , int wid0) {
;     ...
; #pragma unroll 16
;     for (int j = 0; j < 64; ++j) {
;         const float wa = w3[j * 1024 + tid], wb = w3[j * 1024 + 512 + tid];
; #pragma unroll
;         for (int g = 0; g < 8; ++g) { const f32x4 hv = *(const f32x4*)(hidT + j * 32 + 4 * g);
; #pragma unroll
;             for (int i = 0; i < 4; ++i) { acc0[4 * g + i] += hv[i] * wa; acc1[4 * g + i] += hv[i] * wb; } }
;     }
;     const float dmin = -3.0701134573253945f, dmax = -15.350567286626973f;
;     const float delta = fabsf(dmin + (float)tid * ((dmax - dmin) / 511.f));
; #pragma unroll
;     for (int g = 0; g < 8; ++g) { f32x4 o0, o1;
; #pragma unroll
;         for (int i = 0; i < 4; ++i) { const float tn = (float)(t0 + 4 * g + i) / (float)(Lf - 1); const float wdw = __expf(-tn * delta); o0[i] = acc0[4 * g + i] * wdw; o1[i] = acc1[4 * g + i] * wdw; }
	ds_read_b128 v[142:145], v186 offset:128
	ds_read_b128 v[146:149], v186 offset:144
	ds_read_b128 v[150:153], v186 offset:160
	ds_read_b128 v[154:157], v186 offset:176
	ds_read_b128 v[158:161], v186 offset:192
	ds_read_b128 v[162:165], v186 offset:208
	ds_read_b128 v[166:169], v186 offset:224
	ds_read_b128 v[170:173], v186 offset:240
	s_waitcnt vmcnt(2) lgkmcnt(8)
	v_pk_fma_f32 v[68:69], v[174:175], v[110:111], v[68:69] op_sel_hi:[0,1,1]
	v_pk_fma_f32 v[62:63], v[176:177], v[110:111], v[62:63] op_sel_hi:[0,1,1]
	v_pk_fma_f32 v[66:67], v[174:175], v[112:113], v[66:67] op_sel_hi:[0,1,1]
	v_pk_fma_f32 v[64:65], v[176:177], v[112:113], v[64:65] op_sel_hi:[0,1,1]
	v_pk_fma_f32 v[60:61], v[174:175], v[114:115], v[60:61] op_sel_hi:[0,1,1]
	v_pk_fma_f32 v[56:57], v[176:177], v[114:115], v[56:57] op_sel_hi:[0,1,1]
	v_pk_fma_f32 v[58:59], v[174:175], v[116:117], v[58:59] op_sel_hi:[0,1,1]
	v_pk_fma_f32 v[54:55], v[176:177], v[116:117], v[54:55] op_sel_hi:[0,1,1]
	v_pk_fma_f32 v[52:53], v[174:175], v[118:119], v[52:53] op_sel_hi:[0,1,1]
	v_pk_fma_f32 v[48:49], v[176:177], v[118:119], v[48:49] op_sel_hi:[0,1,1]
	v_pk_fma_f32 v[50:51], v[174:175], v[120:121], v[50:51] op_sel_hi:[0,1,1]
	v_pk_fma_f32 v[46:47], v[176:177], v[120:121], v[46:47] op_sel_hi:[0,1,1]
	v_pk_fma_f32 v[44:45], v[174:175], v[122:123], v[44:45] op_sel_hi:[0,1,1]
	v_pk_fma_f32 v[40:41], v[176:177], v[122:123], v[40:41] op_sel_hi:[0,1,1]
	v_pk_fma_f32 v[42:43], v[174:175], v[124:125], v[42:43] op_sel_hi:[0,1,1]
	v_pk_fma_f32 v[38:39], v[176:177], v[124:125], v[38:39] op_sel_hi:[0,1,1]
	v_pk_fma_f32 v[36:37], v[174:175], v[126:127], v[36:37] op_sel_hi:[0,1,1]
	v_pk_fma_f32 v[32:33], v[176:177], v[126:127], v[32:33] op_sel_hi:[0,1,1]
	v_pk_fma_f32 v[34:35], v[174:175], v[128:129], v[34:35] op_sel_hi:[0,1,1]
	v_pk_fma_f32 v[30:31], v[176:177], v[128:129], v[30:31] op_sel_hi:[0,1,1]
	v_pk_fma_f32 v[28:29], v[174:175], v[130:131], v[28:29] op_sel_hi:[0,1,1]
	v_pk_fma_f32 v[24:25], v[176:177], v[130:131], v[24:25] op_sel_hi:[0,1,1]
	v_pk_fma_f32 v[26:27], v[174:175], v[132:133], v[26:27] op_sel_hi:[0,1,1]
	v_pk_fma_f32 v[22:23], v[176:177], v[132:133], v[22:23] op_sel_hi:[0,1,1]
	v_pk_fma_f32 v[20:21], v[174:175], v[134:135], v[20:21] op_sel_hi:[0,1,1]
	v_pk_fma_f32 v[14:15], v[176:177], v[134:135], v[14:15] op_sel_hi:[0,1,1]
	v_pk_fma_f32 v[18:19], v[174:175], v[136:137], v[18:19] op_sel_hi:[0,1,1]
	v_pk_fma_f32 v[16:17], v[176:177], v[136:137], v[16:17] op_sel_hi:[0,1,1]
	v_pk_fma_f32 v[10:11], v[174:175], v[138:139], v[10:11] op_sel_hi:[0,1,1]
	v_pk_fma_f32 v[6:7], v[176:177], v[138:139], v[6:7] op_sel_hi:[0,1,1]
	v_pk_fma_f32 v[12:13], v[174:175], v[140:141], v[12:13] op_sel_hi:[0,1,1]
	v_pk_fma_f32 v[8:9], v[176:177], v[140:141], v[8:9] op_sel_hi:[0,1,1]
	s_waitcnt vmcnt(0) lgkmcnt(0)
	v_pk_fma_f32 v[68:69], v[178:179], v[142:143], v[68:69] op_sel_hi:[0,1,1]
	v_pk_fma_f32 v[62:63], v[180:181], v[142:143], v[62:63] op_sel_hi:[0,1,1]
	v_pk_fma_f32 v[66:67], v[178:179], v[144:145], v[66:67] op_sel_hi:[0,1,1]
	v_pk_fma_f32 v[64:65], v[180:181], v[144:145], v[64:65] op_sel_hi:[0,1,1]
	v_pk_fma_f32 v[60:61], v[178:179], v[146:147], v[60:61] op_sel_hi:[0,1,1]
	v_pk_fma_f32 v[56:57], v[180:181], v[146:147], v[56:57] op_sel_hi:[0,1,1]
	v_pk_fma_f32 v[58:59], v[178:179], v[148:149], v[58:59] op_sel_hi:[0,1,1]
	v_pk_fma_f32 v[54:55], v[180:181], v[148:149], v[54:55] op_sel_hi:[0,1,1]
	v_pk_fma_f32 v[52:53], v[178:179], v[150:151], v[52:53] op_sel_hi:[0,1,1]
	v_pk_fma_f32 v[48:49], v[180:181], v[150:151], v[48:49] op_sel_hi:[0,1,1]
	v_pk_fma_f32 v[50:51], v[178:179], v[152:153], v[50:51] op_sel_hi:[0,1,1]
	v_pk_fma_f32 v[46:47], v[180:181], v[152:153], v[46:47] op_sel_hi:[0,1,1]
	v_pk_fma_f32 v[44:45], v[178:179], v[154:155], v[44:45] op_sel_hi:[0,1,1]
	v_pk_fma_f32 v[40:41], v[180:181], v[154:155], v[40:41] op_sel_hi:[0,1,1]
	v_pk_fma_f32 v[42:43], v[178:179], v[156:157], v[42:43] op_sel_hi:[0,1,1]
	v_pk_fma_f32 v[38:39], v[180:181], v[156:157], v[38:39] op_sel_hi:[0,1,1]
	v_pk_fma_f32 v[36:37], v[178:179], v[158:159], v[36:37] op_sel_hi:[0,1,1]
	v_pk_fma_f32 v[32:33], v[180:181], v[158:159], v[32:33] op_sel_hi:[0,1,1]
	v_pk_fma_f32 v[34:35], v[178:179], v[160:161], v[34:35] op_sel_hi:[0,1,1]
	v_pk_fma_f32 v[30:31], v[180:181], v[160:161], v[30:31] op_sel_hi:[0,1,1]
	v_pk_fma_f32 v[28:29], v[178:179], v[162:163], v[28:29] op_sel_hi:[0,1,1]
	v_pk_fma_f32 v[24:25], v[180:181], v[162:163], v[24:25] op_sel_hi:[0,1,1]
	v_pk_fma_f32 v[26:27], v[178:179], v[164:165], v[26:27] op_sel_hi:[0,1,1]
	v_pk_fma_f32 v[22:23], v[180:181], v[164:165], v[22:23] op_sel_hi:[0,1,1]
	v_pk_fma_f32 v[20:21], v[178:179], v[166:167], v[20:21] op_sel_hi:[0,1,1]
	v_pk_fma_f32 v[14:15], v[180:181], v[166:167], v[14:15] op_sel_hi:[0,1,1]
	v_pk_fma_f32 v[18:19], v[178:179], v[168:169], v[18:19] op_sel_hi:[0,1,1]
	v_pk_fma_f32 v[16:17], v[180:181], v[168:169], v[16:17] op_sel_hi:[0,1,1]
	v_pk_fma_f32 v[10:11], v[178:179], v[170:171], v[10:11] op_sel_hi:[0,1,1]
	v_pk_fma_f32 v[6:7], v[180:181], v[170:171], v[6:7] op_sel_hi:[0,1,1]
	v_pk_fma_f32 v[12:13], v[178:179], v[172:173], v[12:13] op_sel_hi:[0,1,1]
	v_pk_fma_f32 v[8:9], v[180:181], v[172:173], v[8:9] op_sel_hi:[0,1,1]
	s_mov_b32 s0, 0
	v_add_u32_e32 v4, 0x10000, v4
	v_cvt_f32_i32_e32 v5, s74
	s_mov_b32 s6, 0xc5fff800
	v_ashrrev_i32_e32 v3, 31, v2
	v_readlane_b32 s4, v252, 32
	v_div_scale_f32 v70, s[38:39], s6, s6, v5
	v_rcp_f32_e32 v71, v70
	v_cvt_f32_i32_e32 v4, v0
	v_lshlrev_b64 v[0:1], 15, v[0:1]
	v_readlane_b32 s5, v252, 33
	v_fma_f32 v72, -v70, v71, 1.0
	s_ashr_i32 s75, s74, 31
	v_lshlrev_b64 v[2:3], 15, v[2:3]
	v_fmac_f32_e32 v71, v72, v71
	v_div_scale_f32 v72, vcc, v5, s6, v5
; __device__ __forceinline__ void filter_item(const Params& p, int l, int Lf, int t0, float* dst, float* hidT  , int wid0) {
;     ...
;     const float dmin = -3.0701134573253945f, dmax = -15.350567286626973f;
;     const float delta = fabsf(dmin + (float)tid * ((dmax - dmin) / 511.f));
; #pragma unroll
;     for (int g = 0; g < 8; ++g) { f32x4 o0, o1;
; #pragma unroll
;         for (int i = 0; i < 4; ++i) { const float tn = (float)(t0 + 4 * g + i) / (float)(Lf - 1); const float wdw = __expf(-tn * delta); o0[i] = acc0[4 * g + i] * wdw; o1[i] = acc1[4 * g + i] * wdw; }
;         *(f32x4*)(dst + (size_t)tid * Lf + t0 + 4 * g) = o0; *(f32x4*)(dst + (size_t)(512 + tid) * Lf + t0 + 4 * g) = o1; }
	v_lshl_add_u64 v[0:1], s[4:5], 0, v[0:1]
	s_lshl_b64 s[0:1], s[74:75], 2
	v_lshl_add_u64 v[2:3], s[4:5], 0, v[2:3]
	v_mul_f32_e32 v73, v72, v71
	v_lshl_add_u64 v[0:1], v[0:1], 0, s[0:1]
	v_lshl_add_u64 v[2:3], v[2:3], 0, s[0:1]
	v_fma_f32 v74, -v70, v73, v72
	s_or_b32 s0, s74, 1
	v_fmac_f32_e32 v73, v74, v71
	v_cvt_f32_i32_e32 v74, s0
	v_fma_f32 v70, -v70, v73, v72
	v_div_fmas_f32 v70, v70, v71, v73
	v_div_fixup_f32 v5, v70, s6, v5
	v_div_scale_f32 v70, s[0:1], s6, s6, v74
	v_rcp_f32_e32 v71, v70
	v_fmamk_f32 v4, v4, 0xbcc4df2d, v219
	v_mul_f32_e64 v5, v5, |v4|
	v_mul_f32_e32 v5, 0x3fb8aa3b, v5
	v_exp_f32_e32 v72, v5
	v_fma_f32 v5, -v70, v71, 1.0
	v_fmac_f32_e32 v71, v5, v71
	v_div_scale_f32 v5, vcc, v74, s6, v74
	v_mul_f32_e32 v73, v5, v71
	v_fma_f32 v75, -v70, v73, v5
	v_fmac_f32_e32 v73, v75, v71
	s_or_b32 s0, s74, 2
	v_fma_f32 v5, -v70, v73, v5
	v_cvt_f32_i32_e32 v70, s0
	v_div_fmas_f32 v5, v5, v71, v73
	v_div_fixup_f32 v5, v5, s6, v74
	v_mul_f32_e64 v5, v5, |v4|
	v_div_scale_f32 v71, s[0:1], s6, s6, v70
	v_rcp_f32_e32 v74, v71
	v_mul_f32_e32 v5, 0x3fb8aa3b, v5
	v_exp_f32_e32 v73, v5
	s_or_b32 s0, s74, 3
	v_fma_f32 v5, -v71, v74, 1.0
	v_fmac_f32_e32 v74, v5, v74
	v_div_scale_f32 v5, vcc, v70, s6, v70
	v_mul_f32_e32 v75, v5, v74
	v_fma_f32 v76, -v71, v75, v5
	v_fmac_f32_e32 v75, v76, v74
	v_fma_f32 v5, -v71, v75, v5
	v_cvt_f32_i32_e32 v71, s0
	v_div_fmas_f32 v5, v5, v74, v75
	v_div_fixup_f32 v5, v5, s6, v70
	v_mul_f32_e64 v5, v5, |v4|
	v_div_scale_f32 v70, s[0:1], s6, s6, v71
	v_rcp_f32_e32 v75, v70
	v_mul_f32_e32 v5, 0x3fb8aa3b, v5
	v_exp_f32_e32 v74, v5
	s_or_b32 s0, s74, 4
	v_fma_f32 v5, -v70, v75, 1.0
	v_fmac_f32_e32 v75, v5, v75
	v_div_scale_f32 v5, vcc, v71, s6, v71
	v_mul_f32_e32 v76, v5, v75
	v_fma_f32 v77, -v70, v76, v5
	v_fmac_f32_e32 v76, v77, v75
	v_fma_f32 v5, -v70, v76, v5
	v_div_fmas_f32 v5, v5, v75, v76
	v_div_fixup_f32 v5, v5, s6, v71
	v_mul_f32_e64 v5, v5, |v4|
	v_mul_f32_e32 v5, 0x3fb8aa3b, v5
	v_exp_f32_e32 v75, v5
	v_cvt_f32_i32_e32 v5, s0
	v_pk_mul_f32 v[68:69], v[72:73], v[68:69]
	v_pk_mul_f32 v[62:63], v[72:73], v[62:63]
	v_pk_mul_f32 v[70:71], v[74:75], v[66:67]
	v_div_scale_f32 v66, s[0:1], s6, s6, v5
	v_rcp_f32_e32 v67, v66
	v_pk_mul_f32 v[64:65], v[74:75], v[64:65]
	global_store_dwordx4 v[0:1], v[68:71], off
	global_store_dwordx4 v[2:3], v[62:65], off
	s_or_b32 s0, s74, 5
	s_add_i32 s26, s26, s24
	v_fma_f32 v62, -v66, v67, 1.0
	v_fmac_f32_e32 v67, v62, v67
	v_div_scale_f32 v62, vcc, v5, s6, v5
	v_mul_f32_e32 v63, v62, v67
	v_fma_f32 v64, -v66, v63, v62
	v_cvt_f32_i32_e32 v65, s0
	v_fmac_f32_e32 v63, v64, v67
	v_fma_f32 v62, -v66, v63, v62
	v_div_fmas_f32 v62, v62, v67, v63
	v_div_fixup_f32 v5, v62, s6, v5
	v_div_scale_f32 v62, s[0:1], s6, s6, v65
	v_rcp_f32_e32 v63, v62
	v_mul_f32_e64 v5, v5, |v4|
	v_mul_f32_e32 v5, 0x3fb8aa3b, v5
	v_exp_f32_e32 v64, v5
	v_fma_f32 v5, -v62, v63, 1.0
	v_fmac_f32_e32 v63, v5, v63
	v_div_scale_f32 v5, vcc, v65, s6, v65
	v_mul_f32_e32 v66, v5, v63
	v_fma_f32 v67, -v62, v66, v5
	v_fmac_f32_e32 v66, v67, v63
	s_or_b32 s0, s74, 6
	v_fma_f32 v5, -v62, v66, v5
	v_cvt_f32_i32_e32 v62, s0
	v_div_fmas_f32 v5, v5, v63, v66
	v_div_fixup_f32 v5, v5, s6, v65
	v_mul_f32_e64 v5, v5, |v4|
	v_div_scale_f32 v63, s[0:1], s6, s6, v62
	v_rcp_f32_e32 v66, v63
	v_mul_f32_e32 v5, 0x3fb8aa3b, v5
	v_exp_f32_e32 v65, v5
	s_or_b32 s0, s74, 7
	v_fma_f32 v5, -v63, v66, 1.0
	v_fmac_f32_e32 v66, v5, v66
	v_div_scale_f32 v5, vcc, v62, s6, v62
	v_mul_f32_e32 v67, v5, v66
	v_fma_f32 v68, -v63, v67, v5
	v_fmac_f32_e32 v67, v68, v66
	v_fma_f32 v5, -v63, v67, v5
	v_cvt_f32_i32_e32 v63, s0
	v_div_fmas_f32 v5, v5, v66, v67
	v_div_fixup_f32 v5, v5, s6, v62
	v_mul_f32_e64 v5, v5, |v4|
	v_div_scale_f32 v62, s[0:1], s6, s6, v63
	v_rcp_f32_e32 v67, v62
	v_mul_f32_e32 v5, 0x3fb8aa3b, v5
	v_exp_f32_e32 v66, v5
	s_or_b32 s0, s74, 8
	v_fma_f32 v5, -v62, v67, 1.0
	v_fmac_f32_e32 v67, v5, v67
	v_div_scale_f32 v5, vcc, v63, s6, v63
	v_mul_f32_e32 v68, v5, v67
	v_fma_f32 v69, -v62, v68, v5
	v_fmac_f32_e32 v68, v69, v67
	v_fma_f32 v5, -v62, v68, v5
	v_div_fmas_f32 v5, v5, v67, v68
	v_div_fixup_f32 v5, v5, s6, v63
	v_mul_f32_e64 v5, v5, |v4|
	v_mul_f32_e32 v5, 0x3fb8aa3b, v5
	v_exp_f32_e32 v67, v5
	v_cvt_f32_i32_e32 v5, s0
	v_pk_mul_f32 v[60:61], v[64:65], v[60:61]
	v_pk_mul_f32 v[56:57], v[64:65], v[56:57]
	v_pk_mul_f32 v[62:63], v[66:67], v[58:59]
	v_div_scale_f32 v64, s[0:1], s6, s6, v5
	v_rcp_f32_e32 v65, v64
	v_pk_mul_f32 v[58:59], v[66:67], v[54:55]
	s_or_b32 s0, s74, 9
	global_store_dwordx4 v[0:1], v[60:63], off offset:16
	global_store_dwordx4 v[2:3], v[56:59], off offset:16
	v_fma_f32 v54, -v64, v65, 1.0
	v_fmac_f32_e32 v65, v54, v65
	v_div_scale_f32 v54, vcc, v5, s6, v5
	v_mul_f32_e32 v55, v54, v65
	v_fma_f32 v56, -v64, v55, v54
	v_cvt_f32_i32_e32 v57, s0
	v_fmac_f32_e32 v55, v56, v65
	v_fma_f32 v54, -v64, v55, v54
	v_div_fmas_f32 v54, v54, v65, v55
	v_div_fixup_f32 v5, v54, s6, v5
	v_div_scale_f32 v54, s[0:1], s6, s6, v57
	v_rcp_f32_e32 v55, v54
	v_mul_f32_e64 v5, v5, |v4|
	v_mul_f32_e32 v5, 0x3fb8aa3b, v5
	v_exp_f32_e32 v56, v5
	v_fma_f32 v5, -v54, v55, 1.0
	v_fmac_f32_e32 v55, v5, v55
	v_div_scale_f32 v5, vcc, v57, s6, v57
	v_mul_f32_e32 v58, v5, v55
	v_fma_f32 v59, -v54, v58, v5
	v_fmac_f32_e32 v58, v59, v55
	s_or_b32 s0, s74, 10
	v_fma_f32 v5, -v54, v58, v5
	v_cvt_f32_i32_e32 v54, s0
	v_div_fmas_f32 v5, v5, v55, v58
	v_div_fixup_f32 v5, v5, s6, v57
	v_mul_f32_e64 v5, v5, |v4|
	v_div_scale_f32 v55, s[0:1], s6, s6, v54
	v_rcp_f32_e32 v58, v55
	v_mul_f32_e32 v5, 0x3fb8aa3b, v5
	v_exp_f32_e32 v57, v5
	s_or_b32 s0, s74, 11
	v_fma_f32 v5, -v55, v58, 1.0
	v_fmac_f32_e32 v58, v5, v58
	v_div_scale_f32 v5, vcc, v54, s6, v54
; __device__ __forceinline__ void filter_item(const Params& p, int l, int Lf, int t0, float* dst, float* hidT  , int wid0) {
;     ...
;     const float dmin = -3.0701134573253945f, dmax = -15.350567286626973f;
;     const float delta = fabsf(dmin + (float)tid * ((dmax - dmin) / 511.f));
; #pragma unroll
;     for (int g = 0; g < 8; ++g) { f32x4 o0, o1;
; #pragma unroll
;         for (int i = 0; i < 4; ++i) { const float tn = (float)(t0 + 4 * g + i) / (float)(Lf - 1); const float wdw = __expf(-tn * delta); o0[i] = acc0[4 * g + i] * wdw; o1[i] = acc1[4 * g + i] * wdw; }
;         *(f32x4*)(dst + (size_t)tid * Lf + t0 + 4 * g) = o0; *(f32x4*)(dst + (size_t)(512 + tid) * Lf + t0 + 4 * g) = o1; }
	v_mul_f32_e32 v59, v5, v58
	v_fma_f32 v60, -v55, v59, v5
	v_fmac_f32_e32 v59, v60, v58
	v_fma_f32 v5, -v55, v59, v5
	v_cvt_f32_i32_e32 v55, s0
	v_div_fmas_f32 v5, v5, v58, v59
	v_div_fixup_f32 v5, v5, s6, v54
	v_mul_f32_e64 v5, v5, |v4|
	v_div_scale_f32 v54, s[0:1], s6, s6, v55
	v_rcp_f32_e32 v59, v54
	v_mul_f32_e32 v5, 0x3fb8aa3b, v5
	v_exp_f32_e32 v58, v5
	s_or_b32 s0, s74, 12
	v_fma_f32 v5, -v54, v59, 1.0
	v_fmac_f32_e32 v59, v5, v59
	v_div_scale_f32 v5, vcc, v55, s6, v55
	v_mul_f32_e32 v60, v5, v59
	v_fma_f32 v61, -v54, v60, v5
	v_fmac_f32_e32 v60, v61, v59
	v_fma_f32 v5, -v54, v60, v5
	v_div_fmas_f32 v5, v5, v59, v60
	v_div_fixup_f32 v5, v5, s6, v55
	v_mul_f32_e64 v5, v5, |v4|
	v_mul_f32_e32 v5, 0x3fb8aa3b, v5
	v_exp_f32_e32 v59, v5
	v_cvt_f32_i32_e32 v5, s0
	v_pk_mul_f32 v[52:53], v[56:57], v[52:53]
	v_pk_mul_f32 v[48:49], v[56:57], v[48:49]
	v_pk_mul_f32 v[54:55], v[58:59], v[50:51]
	v_div_scale_f32 v56, s[0:1], s6, s6, v5
	v_rcp_f32_e32 v57, v56
	v_pk_mul_f32 v[50:51], v[58:59], v[46:47]
	s_or_b32 s0, s74, 13
	global_store_dwordx4 v[0:1], v[52:55], off offset:32
	global_store_dwordx4 v[2:3], v[48:51], off offset:32
	v_fma_f32 v46, -v56, v57, 1.0
	v_fmac_f32_e32 v57, v46, v57
	v_div_scale_f32 v46, vcc, v5, s6, v5
	v_mul_f32_e32 v47, v46, v57
	v_fma_f32 v48, -v56, v47, v46
	v_cvt_f32_i32_e32 v49, s0
	v_fmac_f32_e32 v47, v48, v57
	v_fma_f32 v46, -v56, v47, v46
	v_div_fmas_f32 v46, v46, v57, v47
	v_div_fixup_f32 v5, v46, s6, v5
	v_div_scale_f32 v46, s[0:1], s6, s6, v49
	v_rcp_f32_e32 v47, v46
	v_mul_f32_e64 v5, v5, |v4|
	v_mul_f32_e32 v5, 0x3fb8aa3b, v5
	v_exp_f32_e32 v48, v5
	v_fma_f32 v5, -v46, v47, 1.0
	v_fmac_f32_e32 v47, v5, v47
	v_div_scale_f32 v5, vcc, v49, s6, v49
	v_mul_f32_e32 v50, v5, v47
	v_fma_f32 v51, -v46, v50, v5
	v_fmac_f32_e32 v50, v51, v47
	s_or_b32 s0, s74, 14
	v_fma_f32 v5, -v46, v50, v5
	v_cvt_f32_i32_e32 v46, s0
	v_div_fmas_f32 v5, v5, v47, v50
	v_div_fixup_f32 v5, v5, s6, v49
	v_mul_f32_e64 v5, v5, |v4|
	v_div_scale_f32 v47, s[0:1], s6, s6, v46
	v_rcp_f32_e32 v50, v47
	v_mul_f32_e32 v5, 0x3fb8aa3b, v5
	v_exp_f32_e32 v49, v5
	s_or_b32 s0, s74, 15
	v_fma_f32 v5, -v47, v50, 1.0
	v_fmac_f32_e32 v50, v5, v50
	v_div_scale_f32 v5, vcc, v46, s6, v46
	v_mul_f32_e32 v51, v5, v50
	v_fma_f32 v52, -v47, v51, v5
	v_fmac_f32_e32 v51, v52, v50
	v_fma_f32 v5, -v47, v51, v5
	v_cvt_f32_i32_e32 v47, s0
	v_div_fmas_f32 v5, v5, v50, v51
	v_div_fixup_f32 v5, v5, s6, v46
	v_mul_f32_e64 v5, v5, |v4|
	v_div_scale_f32 v46, s[0:1], s6, s6, v47
	v_rcp_f32_e32 v51, v46
	v_mul_f32_e32 v5, 0x3fb8aa3b, v5
	v_exp_f32_e32 v50, v5
	s_or_b32 s0, s74, 16
	v_fma_f32 v5, -v46, v51, 1.0
	v_fmac_f32_e32 v51, v5, v51
	v_div_scale_f32 v5, vcc, v47, s6, v47
	v_mul_f32_e32 v52, v5, v51
	v_fma_f32 v53, -v46, v52, v5
	v_fmac_f32_e32 v52, v53, v51
	v_fma_f32 v5, -v46, v52, v5
	v_div_fmas_f32 v5, v5, v51, v52
	v_div_fixup_f32 v5, v5, s6, v47
	v_mul_f32_e64 v5, v5, |v4|
	v_mul_f32_e32 v5, 0x3fb8aa3b, v5
	v_exp_f32_e32 v51, v5
	v_cvt_f32_i32_e32 v5, s0
	v_pk_mul_f32 v[44:45], v[48:49], v[44:45]
	v_pk_mul_f32 v[40:41], v[48:49], v[40:41]
	v_pk_mul_f32 v[46:47], v[50:51], v[42:43]
	v_div_scale_f32 v48, s[0:1], s6, s6, v5
	v_rcp_f32_e32 v49, v48
	v_pk_mul_f32 v[42:43], v[50:51], v[38:39]
	s_or_b32 s0, s74, 17
	global_store_dwordx4 v[0:1], v[44:47], off offset:48
	global_store_dwordx4 v[2:3], v[40:43], off offset:48
	v_fma_f32 v38, -v48, v49, 1.0
	v_fmac_f32_e32 v49, v38, v49
	v_div_scale_f32 v38, vcc, v5, s6, v5
	v_mul_f32_e32 v39, v38, v49
	v_fma_f32 v40, -v48, v39, v38
	v_cvt_f32_i32_e32 v41, s0
	v_fmac_f32_e32 v39, v40, v49
	v_fma_f32 v38, -v48, v39, v38
	v_div_fmas_f32 v38, v38, v49, v39
	v_div_fixup_f32 v5, v38, s6, v5
	v_div_scale_f32 v38, s[0:1], s6, s6, v41
	v_rcp_f32_e32 v39, v38
	v_mul_f32_e64 v5, v5, |v4|
	v_mul_f32_e32 v5, 0x3fb8aa3b, v5
	v_exp_f32_e32 v40, v5
	v_fma_f32 v5, -v38, v39, 1.0
	v_fmac_f32_e32 v39, v5, v39
	v_div_scale_f32 v5, vcc, v41, s6, v41
	v_mul_f32_e32 v42, v5, v39
	v_fma_f32 v43, -v38, v42, v5
	v_fmac_f32_e32 v42, v43, v39
	s_or_b32 s0, s74, 18
	v_fma_f32 v5, -v38, v42, v5
	v_cvt_f32_i32_e32 v38, s0
	v_div_fmas_f32 v5, v5, v39, v42
	v_div_fixup_f32 v5, v5, s6, v41
	v_mul_f32_e64 v5, v5, |v4|
	v_div_scale_f32 v39, s[0:1], s6, s6, v38
	v_rcp_f32_e32 v42, v39
	v_mul_f32_e32 v5, 0x3fb8aa3b, v5
	v_exp_f32_e32 v41, v5
	s_or_b32 s0, s74, 19
	v_fma_f32 v5, -v39, v42, 1.0
	v_fmac_f32_e32 v42, v5, v42
	v_div_scale_f32 v5, vcc, v38, s6, v38
	v_mul_f32_e32 v43, v5, v42
	v_fma_f32 v44, -v39, v43, v5
	v_fmac_f32_e32 v43, v44, v42
	v_fma_f32 v5, -v39, v43, v5
	v_cvt_f32_i32_e32 v39, s0
	v_div_fmas_f32 v5, v5, v42, v43
	v_div_fixup_f32 v5, v5, s6, v38
	v_mul_f32_e64 v5, v5, |v4|
	v_div_scale_f32 v38, s[0:1], s6, s6, v39
	v_rcp_f32_e32 v43, v38
	v_mul_f32_e32 v5, 0x3fb8aa3b, v5
	v_exp_f32_e32 v42, v5
	s_or_b32 s0, s74, 20
	v_fma_f32 v5, -v38, v43, 1.0
	v_fmac_f32_e32 v43, v5, v43
	v_div_scale_f32 v5, vcc, v39, s6, v39
	v_mul_f32_e32 v44, v5, v43
	v_fma_f32 v45, -v38, v44, v5
	v_fmac_f32_e32 v44, v45, v43
	v_fma_f32 v5, -v38, v44, v5
	v_div_fmas_f32 v5, v5, v43, v44
	v_div_fixup_f32 v5, v5, s6, v39
	v_mul_f32_e64 v5, v5, |v4|
	v_mul_f32_e32 v5, 0x3fb8aa3b, v5
	v_exp_f32_e32 v43, v5
	v_cvt_f32_i32_e32 v5, s0
	v_pk_mul_f32 v[36:37], v[40:41], v[36:37]
	v_pk_mul_f32 v[32:33], v[40:41], v[32:33]
	v_pk_mul_f32 v[38:39], v[42:43], v[34:35]
	v_div_scale_f32 v40, s[0:1], s6, s6, v5
	v_rcp_f32_e32 v41, v40
	v_pk_mul_f32 v[34:35], v[42:43], v[30:31]
	s_or_b32 s0, s74, 21
	global_store_dwordx4 v[0:1], v[36:39], off offset:64
	global_store_dwordx4 v[2:3], v[32:35], off offset:64
	v_fma_f32 v30, -v40, v41, 1.0
	v_fmac_f32_e32 v41, v30, v41
; __device__ __forceinline__ void filter_item(const Params& p, int l, int Lf, int t0, float* dst, float* hidT  , int wid0) {
;     ...
;     const float dmin = -3.0701134573253945f, dmax = -15.350567286626973f;
;     const float delta = fabsf(dmin + (float)tid * ((dmax - dmin) / 511.f));
; #pragma unroll
;     for (int g = 0; g < 8; ++g) { f32x4 o0, o1;
; #pragma unroll
;         for (int i = 0; i < 4; ++i) { const float tn = (float)(t0 + 4 * g + i) / (float)(Lf - 1); const float wdw = __expf(-tn * delta); o0[i] = acc0[4 * g + i] * wdw; o1[i] = acc1[4 * g + i] * wdw; }
;         *(f32x4*)(dst + (size_t)tid * Lf + t0 + 4 * g) = o0; *(f32x4*)(dst + (size_t)(512 + tid) * Lf + t0 + 4 * g) = o1; }
;     __syncthreads();
; __device__ __forceinline__ void phaseA(const Params& p, int l, unsigned char* lds, int wid0) {
;     ...
;     { float* hidT = (float*)(lds + 104448);
;       for (int it = blockIdx.x; it < 256; it += gridDim.x) filter_item(p, l, SEQ, 32 * it, (float*)(ws + WS_FILT), hidT, wid0);
;       }
	v_div_scale_f32 v30, vcc, v5, s6, v5
	v_mul_f32_e32 v31, v30, v41
	v_fma_f32 v32, -v40, v31, v30
	v_cvt_f32_i32_e32 v33, s0
	v_fmac_f32_e32 v31, v32, v41
	v_fma_f32 v30, -v40, v31, v30
	v_div_fmas_f32 v30, v30, v41, v31
	v_div_fixup_f32 v5, v30, s6, v5
	v_div_scale_f32 v30, s[0:1], s6, s6, v33
	v_rcp_f32_e32 v31, v30
	v_mul_f32_e64 v5, v5, |v4|
	v_mul_f32_e32 v5, 0x3fb8aa3b, v5
	v_exp_f32_e32 v32, v5
	v_fma_f32 v5, -v30, v31, 1.0
	v_fmac_f32_e32 v31, v5, v31
	v_div_scale_f32 v5, vcc, v33, s6, v33
	v_mul_f32_e32 v34, v5, v31
	v_fma_f32 v35, -v30, v34, v5
	v_fmac_f32_e32 v34, v35, v31
	s_or_b32 s0, s74, 22
	v_fma_f32 v5, -v30, v34, v5
	v_cvt_f32_i32_e32 v30, s0
	v_div_fmas_f32 v5, v5, v31, v34
	v_div_fixup_f32 v5, v5, s6, v33
	v_mul_f32_e64 v5, v5, |v4|
	v_div_scale_f32 v31, s[0:1], s6, s6, v30
	v_rcp_f32_e32 v34, v31
	v_mul_f32_e32 v5, 0x3fb8aa3b, v5
	v_exp_f32_e32 v33, v5
	s_or_b32 s0, s74, 23
	v_fma_f32 v5, -v31, v34, 1.0
	v_fmac_f32_e32 v34, v5, v34
	v_div_scale_f32 v5, vcc, v30, s6, v30
	v_mul_f32_e32 v35, v5, v34
	v_fma_f32 v36, -v31, v35, v5
	v_fmac_f32_e32 v35, v36, v34
	v_fma_f32 v5, -v31, v35, v5
	v_cvt_f32_i32_e32 v31, s0
	v_div_fmas_f32 v5, v5, v34, v35
	v_div_fixup_f32 v5, v5, s6, v30
	v_mul_f32_e64 v5, v5, |v4|
	v_div_scale_f32 v30, s[0:1], s6, s6, v31
	v_rcp_f32_e32 v35, v30
	v_mul_f32_e32 v5, 0x3fb8aa3b, v5
	v_exp_f32_e32 v34, v5
	s_or_b32 s0, s74, 24
	v_fma_f32 v5, -v30, v35, 1.0
	v_fmac_f32_e32 v35, v5, v35
	v_div_scale_f32 v5, vcc, v31, s6, v31
	v_mul_f32_e32 v36, v5, v35
	v_fma_f32 v37, -v30, v36, v5
	v_fmac_f32_e32 v36, v37, v35
	v_fma_f32 v5, -v30, v36, v5
	v_div_fmas_f32 v5, v5, v35, v36
	v_div_fixup_f32 v5, v5, s6, v31
	v_mul_f32_e64 v5, v5, |v4|
	v_mul_f32_e32 v5, 0x3fb8aa3b, v5
	v_exp_f32_e32 v35, v5
	v_cvt_f32_i32_e32 v5, s0
	v_pk_mul_f32 v[28:29], v[32:33], v[28:29]
	v_pk_mul_f32 v[24:25], v[32:33], v[24:25]
	v_pk_mul_f32 v[30:31], v[34:35], v[26:27]
	v_div_scale_f32 v32, s[0:1], s6, s6, v5
	v_rcp_f32_e32 v33, v32
	v_pk_mul_f32 v[26:27], v[34:35], v[22:23]
	s_or_b32 s0, s74, 25
	global_store_dwordx4 v[0:1], v[28:31], off offset:80
	global_store_dwordx4 v[2:3], v[24:27], off offset:80
	v_fma_f32 v22, -v32, v33, 1.0
	v_fmac_f32_e32 v33, v22, v33
	v_div_scale_f32 v22, vcc, v5, s6, v5
	v_mul_f32_e32 v23, v22, v33
	v_fma_f32 v24, -v32, v23, v22
	v_cvt_f32_i32_e32 v25, s0
	v_fmac_f32_e32 v23, v24, v33
	v_fma_f32 v22, -v32, v23, v22
	v_div_fmas_f32 v22, v22, v33, v23
	v_div_fixup_f32 v5, v22, s6, v5
	v_div_scale_f32 v22, s[0:1], s6, s6, v25
	v_rcp_f32_e32 v23, v22
	v_mul_f32_e64 v5, v5, |v4|
	v_mul_f32_e32 v5, 0x3fb8aa3b, v5
	v_exp_f32_e32 v24, v5
	v_fma_f32 v5, -v22, v23, 1.0
	v_fmac_f32_e32 v23, v5, v23
	v_div_scale_f32 v5, vcc, v25, s6, v25
	v_mul_f32_e32 v26, v5, v23
	v_fma_f32 v27, -v22, v26, v5
	v_fmac_f32_e32 v26, v27, v23
	s_or_b32 s0, s74, 26
	v_fma_f32 v5, -v22, v26, v5
	v_cvt_f32_i32_e32 v22, s0
	v_div_fmas_f32 v5, v5, v23, v26
	v_div_fixup_f32 v5, v5, s6, v25
	v_mul_f32_e64 v5, v5, |v4|
	v_div_scale_f32 v23, s[0:1], s6, s6, v22
	v_rcp_f32_e32 v26, v23
	v_mul_f32_e32 v5, 0x3fb8aa3b, v5
	v_exp_f32_e32 v25, v5
	s_or_b32 s0, s74, 27
	v_fma_f32 v5, -v23, v26, 1.0
	v_fmac_f32_e32 v26, v5, v26
	v_div_scale_f32 v5, vcc, v22, s6, v22
	v_mul_f32_e32 v27, v5, v26
	v_fma_f32 v28, -v23, v27, v5
	v_fmac_f32_e32 v27, v28, v26
	v_fma_f32 v5, -v23, v27, v5
	v_cvt_f32_i32_e32 v23, s0
	v_div_fmas_f32 v5, v5, v26, v27
	v_div_fixup_f32 v5, v5, s6, v22
	v_mul_f32_e64 v5, v5, |v4|
	v_div_scale_f32 v22, s[0:1], s6, s6, v23
	v_rcp_f32_e32 v27, v22
	v_mul_f32_e32 v5, 0x3fb8aa3b, v5
	v_exp_f32_e32 v26, v5
	s_or_b32 s0, s74, 28
	v_fma_f32 v5, -v22, v27, 1.0
	v_fmac_f32_e32 v27, v5, v27
	v_div_scale_f32 v5, vcc, v23, s6, v23
	v_mul_f32_e32 v28, v5, v27
	v_fma_f32 v29, -v22, v28, v5
	v_fmac_f32_e32 v28, v29, v27
	v_fma_f32 v5, -v22, v28, v5
	v_div_fmas_f32 v5, v5, v27, v28
	v_cvt_f32_i32_e32 v28, s0
	v_div_fixup_f32 v5, v5, s6, v23
	v_mul_f32_e64 v5, v5, |v4|
	v_mul_f32_e32 v5, 0x3fb8aa3b, v5
	v_exp_f32_e32 v27, v5
	v_div_scale_f32 v5, s[0:1], s6, s6, v28
	v_rcp_f32_e32 v29, v5
	v_pk_mul_f32 v[22:23], v[26:27], v[18:19]
	v_pk_mul_f32 v[20:21], v[24:25], v[20:21]
	v_pk_mul_f32 v[14:15], v[24:25], v[14:15]
	v_fma_f32 v18, -v5, v29, 1.0
	v_fmac_f32_e32 v29, v18, v29
	v_div_scale_f32 v18, vcc, v28, s6, v28
	v_mul_f32_e32 v19, v18, v29
	v_fma_f32 v24, -v5, v19, v18
	s_or_b32 s0, s74, 29
	v_fmac_f32_e32 v19, v24, v29
	v_cvt_f32_i32_e32 v24, s0
	v_fma_f32 v5, -v5, v19, v18
	v_div_fmas_f32 v5, v5, v29, v19
	v_div_fixup_f32 v5, v5, s6, v28
	v_div_scale_f32 v19, s[0:1], s6, s6, v24
	v_rcp_f32_e32 v25, v19
	v_mul_f32_e64 v5, v5, |v4|
	v_mul_f32_e32 v5, 0x3fb8aa3b, v5
	v_exp_f32_e32 v18, v5
	v_fma_f32 v5, -v19, v25, 1.0
	v_fmac_f32_e32 v25, v5, v25
	v_div_scale_f32 v5, vcc, v24, s6, v24
	v_pk_mul_f32 v[16:17], v[26:27], v[16:17]
	v_mul_f32_e32 v26, v5, v25
	v_fma_f32 v27, -v19, v26, v5
	s_or_b32 s0, s74, 30
	v_fmac_f32_e32 v26, v27, v25
	v_cvt_f32_i32_e32 v27, s0
	v_fma_f32 v5, -v19, v26, v5
	v_div_fmas_f32 v5, v5, v25, v26
	v_div_fixup_f32 v5, v5, s6, v24
	v_div_scale_f32 v24, s[0:1], s6, s6, v27
	v_rcp_f32_e32 v25, v24
	v_mul_f32_e64 v5, v5, |v4|
	v_mul_f32_e32 v5, 0x3fb8aa3b, v5
	v_exp_f32_e32 v19, v5
	v_fma_f32 v5, -v24, v25, 1.0
	v_fmac_f32_e32 v25, v5, v25
	v_div_scale_f32 v5, vcc, v27, s6, v27
	v_mul_f32_e32 v26, v5, v25
	v_fma_f32 v28, -v24, v26, v5
	s_or_b32 s0, s74, 31
	v_fmac_f32_e32 v26, v28, v25
	v_cvt_f32_i32_e32 v28, s0
	v_fma_f32 v5, -v24, v26, v5
	v_div_fmas_f32 v5, v5, v25, v26
	v_div_fixup_f32 v5, v5, s6, v27
	v_div_scale_f32 v25, s[0:1], s6, s6, v28
	v_rcp_f32_e32 v26, v25
	v_mul_f32_e64 v5, v5, |v4|
	v_mul_f32_e32 v5, 0x3fb8aa3b, v5
	v_exp_f32_e32 v24, v5
	v_fma_f32 v5, -v25, v26, 1.0
	v_fmac_f32_e32 v26, v5, v26
	v_div_scale_f32 v5, vcc, v28, s6, v28
	v_mul_f32_e32 v27, v5, v26
	v_fma_f32 v29, -v25, v27, v5
	v_fmac_f32_e32 v27, v29, v26
	v_fma_f32 v5, -v25, v27, v5
	v_div_fmas_f32 v5, v5, v26, v27
	v_div_fixup_f32 v5, v5, s6, v28
	v_mul_f32_e64 v4, v5, |v4|
	v_mul_f32_e32 v4, 0x3fb8aa3b, v4
	v_exp_f32_e32 v25, v4
	v_pk_mul_f32 v[10:11], v[18:19], v[10:11]
	s_cmpk_gt_i32 s26, 0xff
	s_mov_b32 s75, 0x18000
	v_pk_mul_f32 v[12:13], v[24:25], v[12:13]
	global_store_dwordx4 v[0:1], v[20:23], off offset:96
	global_store_dwordx4 v[2:3], v[14:17], off offset:96
	v_pk_mul_f32 v[4:5], v[18:19], v[6:7]
	v_pk_mul_f32 v[6:7], v[24:25], v[8:9]
	global_store_dwordx4 v[0:1], v[10:13], off offset:112
	global_store_dwordx4 v[2:3], v[4:7], off offset:112
	s_barrier
	s_cbranch_scc0 .LBB0_592
	s_branch .LBB0_725
